# v27: P11 residual epilogue uses the same 16-deep load ring with per-chunk stores (replaces the batched variant), on top of v26
# speedup vs baseline: 1.0019x; 1.0019x over previous
;     __device__ __forceinline__ void operator()(const f32x4 (&acc)[2][2][4][2], const Unit& u, int wr, int wc, int fr, int fq) const {
;         const int row0 = u.pm * 256 + wr * 64 + fr, col0 = u.pn * 256 + wc * 32 + 4 * fq;
; #pragma unroll
;         for (int ai = 0; ai < 2; ++ai)
; #pragma unroll
;             for (int m = 0; m < 4; ++m) {
;                 const size_t off = (size_t)(row0 + ai * 128 + m * 16) * D + col0;
; #pragma unroll
;                 for (int bj = 0; bj < 2; ++bj)
; #pragma unroll
;                     for (int n = 0; n < 2; ++n) { const f32x4 b = *(const f32x4*)(base + off + bj * 128 + n * 16); *(f32x4*)(out + off + bj * 128 + n * 16) = b + acc[ai][bj][m][n]; }
;             }
;     }
.LBB0_1093:
	v_lshl_add_u32 v146, s73, 8, v1
	v_lshl_or_b32 v142, s74, 8, v149
	v_ashrrev_i32_e32 v147, 31, v146
	v_ashrrev_i32_e32 v143, 31, v142
	v_lshlrev_b64 v[144:145], 13, v[146:147]
	v_lshl_add_u64 v[154:155], s[12:13], 0, v[144:145]
	v_lshlrev_b64 v[144:145], 2, v[142:143]
	v_lshl_add_u64 v[142:143], v[154:155], 0, v[144:145]
	v_lshlrev_b32_e32 v250, 13, v146
	v_add_u32_e32 v250, v250, v144
	global_load_dwordx4 v[184:187], v250, s[12:13]
	global_load_dwordx4 v[188:191], v250, s[12:13] offset:64
	global_load_dwordx4 v[192:195], v250, s[12:13] offset:512
	global_load_dwordx4 v[196:199], v250, s[12:13] offset:576
	v_add_u32_e32 v251, 0x20000, v250
	global_load_dwordx4 v[200:203], v251, s[12:13]
	v_add_u32_e32 v251, 0x20000, v250
	global_load_dwordx4 v[204:207], v251, s[12:13] offset:64
	v_add_u32_e32 v251, 0x20000, v250
	global_load_dwordx4 v[208:211], v251, s[12:13] offset:512
	v_add_u32_e32 v251, 0x20000, v250
	global_load_dwordx4 v[212:215], v251, s[12:13] offset:576
	v_add_u32_e32 v251, 0x40000, v250
	global_load_dwordx4 v[216:219], v251, s[12:13]
	v_add_u32_e32 v251, 0x40000, v250
	global_load_dwordx4 v[220:223], v251, s[12:13] offset:64
	v_add_u32_e32 v251, 0x40000, v250
	global_load_dwordx4 v[224:227], v251, s[12:13] offset:512
	v_add_u32_e32 v251, 0x40000, v250
	global_load_dwordx4 v[228:231], v251, s[12:13] offset:576
	v_add_u32_e32 v251, 0x60000, v250
	global_load_dwordx4 v[232:235], v251, s[12:13]
	v_add_u32_e32 v251, 0x60000, v250
	global_load_dwordx4 v[236:239], v251, s[12:13] offset:64
	v_add_u32_e32 v251, 0x60000, v250
	global_load_dwordx4 v[240:243], v251, s[12:13] offset:512
	v_add_u32_e32 v251, 0x60000, v250
	global_load_dwordx4 v[244:247], v251, s[12:13] offset:576
	s_mov_b64 s[48:49], -1
	s_waitcnt vmcnt(15)
	s_nop 1
	v_mov_b64_e32 v[154:155], v[184:185]
	v_mov_b64_e32 v[156:157], v[186:187]
	v_add_u32_e32 v251, 0x100000, v250
	global_load_dwordx4 v[184:187], v251, s[12:13]
	v_pk_add_f32 v[128:129], v[128:129], v[156:157]
	v_pk_add_f32 v[126:127], v[126:127], v[154:155]
	global_store_dwordx4 v[142:143], v[126:129], off
	s_waitcnt vmcnt(15)
	s_nop 1
	v_mov_b64_e32 v[126:127], v[188:189]
	v_mov_b64_e32 v[128:129], v[190:191]
	v_add_u32_e32 v251, 0x100000, v250
	global_load_dwordx4 v[188:191], v251, s[12:13] offset:64
	v_pk_add_f32 v[124:125], v[124:125], v[128:129]
	v_pk_add_f32 v[122:123], v[122:123], v[126:127]
	global_store_dwordx4 v[142:143], v[122:125], off offset:64
	s_waitcnt vmcnt(15)
	s_nop 1
	v_mov_b64_e32 v[122:123], v[192:193]
	v_mov_b64_e32 v[124:125], v[194:195]
	v_add_u32_e32 v251, 0x100000, v250
	global_load_dwordx4 v[192:195], v251, s[12:13] offset:512
	v_pk_add_f32 v[120:121], v[120:121], v[124:125]
	v_pk_add_f32 v[118:119], v[118:119], v[122:123]
	global_store_dwordx4 v[142:143], v[118:121], off offset:512
	s_waitcnt vmcnt(15)
	s_nop 1
	v_mov_b64_e32 v[118:119], v[196:197]
	v_mov_b64_e32 v[120:121], v[198:199]
	v_add_u32_e32 v251, 0x100000, v250
	global_load_dwordx4 v[196:199], v251, s[12:13] offset:576
	v_pk_add_f32 v[112:113], v[112:113], v[120:121]
	v_pk_add_f32 v[110:111], v[110:111], v[118:119]
	global_store_dwordx4 v[142:143], v[110:113], off offset:576
	s_nop 1
	v_or_b32_e32 v110, 16, v146
	v_ashrrev_i32_e32 v111, 31, v110
	v_lshlrev_b64 v[110:111], 13, v[110:111]
	v_lshl_add_u64 v[110:111], s[12:13], 0, v[110:111]
	v_lshl_add_u64 v[118:119], v[110:111], 0, v[144:145]
	s_waitcnt vmcnt(15)
	s_nop 1
	v_mov_b64_e32 v[110:111], v[200:201]
	v_mov_b64_e32 v[112:113], v[202:203]
	v_add_u32_e32 v251, 0x120000, v250
	global_load_dwordx4 v[200:203], v251, s[12:13]
	v_pk_add_f32 v[112:113], v[116:117], v[112:113]
	v_pk_add_f32 v[110:111], v[114:115], v[110:111]
	global_store_dwordx4 v[118:119], v[110:113], off
	s_waitcnt vmcnt(15)
	s_nop 1
	v_mov_b64_e32 v[110:111], v[204:205]
	v_mov_b64_e32 v[112:113], v[206:207]
	v_add_u32_e32 v251, 0x120000, v250
	global_load_dwordx4 v[204:207], v251, s[12:13] offset:64
	v_pk_add_f32 v[108:109], v[108:109], v[112:113]
	v_pk_add_f32 v[106:107], v[106:107], v[110:111]
	global_store_dwordx4 v[118:119], v[106:109], off offset:64
	s_waitcnt vmcnt(15)
	s_nop 1
	v_mov_b64_e32 v[106:107], v[208:209]
	v_mov_b64_e32 v[108:109], v[210:211]
	v_add_u32_e32 v251, 0x120000, v250
	global_load_dwordx4 v[208:211], v251, s[12:13] offset:512
	v_pk_add_f32 v[104:105], v[104:105], v[108:109]
	v_pk_add_f32 v[102:103], v[102:103], v[106:107]
	global_store_dwordx4 v[118:119], v[102:105], off offset:512
	s_waitcnt vmcnt(15)
	s_nop 1
	v_mov_b64_e32 v[102:103], v[212:213]
	v_mov_b64_e32 v[104:105], v[214:215]
	v_add_u32_e32 v251, 0x120000, v250
	global_load_dwordx4 v[212:215], v251, s[12:13] offset:576
	v_pk_add_f32 v[100:101], v[100:101], v[104:105]
	v_pk_add_f32 v[98:99], v[98:99], v[102:103]
	global_store_dwordx4 v[118:119], v[98:101], off offset:576
	s_nop 1
	v_or_b32_e32 v98, 32, v146
	v_ashrrev_i32_e32 v99, 31, v98
	v_lshlrev_b64 v[98:99], 13, v[98:99]
	v_lshl_add_u64 v[98:99], s[12:13], 0, v[98:99]
	v_lshl_add_u64 v[102:103], v[98:99], 0, v[144:145]
	s_waitcnt vmcnt(15)
	s_nop 1
	v_mov_b64_e32 v[98:99], v[216:217]
	v_mov_b64_e32 v[100:101], v[218:219]
	v_add_u32_e32 v251, 0x140000, v250
	global_load_dwordx4 v[216:219], v251, s[12:13]
	v_pk_add_f32 v[96:97], v[96:97], v[100:101]
	v_pk_add_f32 v[94:95], v[94:95], v[98:99]
	global_store_dwordx4 v[102:103], v[94:97], off
	s_waitcnt vmcnt(15)
	s_nop 1
	v_mov_b64_e32 v[94:95], v[220:221]
	v_mov_b64_e32 v[96:97], v[222:223]
	v_add_u32_e32 v251, 0x140000, v250
	global_load_dwordx4 v[220:223], v251, s[12:13] offset:64
	v_pk_add_f32 v[92:93], v[92:93], v[96:97]
	v_pk_add_f32 v[90:91], v[90:91], v[94:95]
	global_store_dwordx4 v[102:103], v[90:93], off offset:64
	s_waitcnt vmcnt(15)
;     __device__ __forceinline__ void operator()(const f32x4 (&acc)[2][2][4][2], const Unit& u, int wr, int wc, int fr, int fq) const {
;     ...
; #pragma unroll
;         for (int ai = 0; ai < 2; ++ai)
; #pragma unroll
;             for (int m = 0; m < 4; ++m) {
;                 const size_t off = (size_t)(row0 + ai * 128 + m * 16) * D + col0;
; #pragma unroll
;                 for (int bj = 0; bj < 2; ++bj)
; #pragma unroll
;                     for (int n = 0; n < 2; ++n) { const f32x4 b = *(const f32x4*)(base + off + bj * 128 + n * 16); *(f32x4*)(out + off + bj * 128 + n * 16) = b + acc[ai][bj][m][n]; }
;             }
;     }
	s_nop 1
	v_mov_b64_e32 v[90:91], v[224:225]
	v_mov_b64_e32 v[92:93], v[226:227]
	v_add_u32_e32 v251, 0x140000, v250
	global_load_dwordx4 v[224:227], v251, s[12:13] offset:512
	v_pk_add_f32 v[88:89], v[88:89], v[92:93]
	v_pk_add_f32 v[86:87], v[86:87], v[90:91]
	global_store_dwordx4 v[102:103], v[86:89], off offset:512
	s_waitcnt vmcnt(15)
	s_nop 1
	v_mov_b64_e32 v[86:87], v[228:229]
	v_mov_b64_e32 v[88:89], v[230:231]
	v_add_u32_e32 v251, 0x140000, v250
	global_load_dwordx4 v[228:231], v251, s[12:13] offset:576
	v_pk_add_f32 v[84:85], v[84:85], v[88:89]
	v_pk_add_f32 v[82:83], v[82:83], v[86:87]
	global_store_dwordx4 v[102:103], v[82:85], off offset:576
	s_nop 1
	v_or_b32_e32 v82, 48, v146
	v_ashrrev_i32_e32 v83, 31, v82
	v_lshlrev_b64 v[82:83], 13, v[82:83]
	v_lshl_add_u64 v[82:83], s[12:13], 0, v[82:83]
	v_lshl_add_u64 v[86:87], v[82:83], 0, v[144:145]
	s_waitcnt vmcnt(15)
	s_nop 1
	v_mov_b64_e32 v[82:83], v[232:233]
	v_mov_b64_e32 v[84:85], v[234:235]
	v_add_u32_e32 v251, 0x160000, v250
	global_load_dwordx4 v[232:235], v251, s[12:13]
	v_pk_add_f32 v[80:81], v[80:81], v[84:85]
	v_pk_add_f32 v[78:79], v[78:79], v[82:83]
	global_store_dwordx4 v[86:87], v[78:81], off
	s_waitcnt vmcnt(15)
	s_nop 1
	v_mov_b64_e32 v[78:79], v[236:237]
	v_mov_b64_e32 v[80:81], v[238:239]
	v_add_u32_e32 v251, 0x160000, v250
	global_load_dwordx4 v[236:239], v251, s[12:13] offset:64
	v_pk_add_f32 v[76:77], v[76:77], v[80:81]
	v_pk_add_f32 v[74:75], v[74:75], v[78:79]
	global_store_dwordx4 v[86:87], v[74:77], off offset:64
	s_waitcnt vmcnt(15)
	s_nop 1
	v_mov_b64_e32 v[74:75], v[240:241]
	v_mov_b64_e32 v[76:77], v[242:243]
	v_add_u32_e32 v251, 0x160000, v250
	global_load_dwordx4 v[240:243], v251, s[12:13] offset:512
	v_pk_add_f32 v[72:73], v[72:73], v[76:77]
	v_pk_add_f32 v[70:71], v[70:71], v[74:75]
	global_store_dwordx4 v[86:87], v[70:73], off offset:512
	s_waitcnt vmcnt(15)
	s_nop 1
	v_mov_b64_e32 v[70:71], v[244:245]
	v_mov_b64_e32 v[72:73], v[246:247]
	v_add_u32_e32 v251, 0x160000, v250
	global_load_dwordx4 v[244:247], v251, s[12:13] offset:576
	v_pk_add_f32 v[68:69], v[68:69], v[72:73]
	v_add_co_u32_e32 v72, vcc, s67, v142
	v_pk_add_f32 v[66:67], v[66:67], v[70:71]
	s_nop 0
	v_addc_co_u32_e32 v73, vcc, 0, v143, vcc
	global_store_dwordx4 v[86:87], v[66:69], off offset:576
	v_lshl_add_u64 v[70:71], v[142:143], 0, s[40:41]
	s_waitcnt vmcnt(15)
	s_nop 1
	v_mov_b64_e32 v[66:67], v[184:185]
	v_mov_b64_e32 v[68:69], v[186:187]
	v_pk_add_f32 v[64:65], v[64:65], v[68:69]
	v_pk_add_f32 v[62:63], v[62:63], v[66:67]
	global_store_dwordx4 v[72:73], v[62:65], off
	s_waitcnt vmcnt(14)
	s_nop 1
	v_mov_b64_e32 v[62:63], v[188:189]
	v_mov_b64_e32 v[64:65], v[190:191]
	v_pk_add_f32 v[60:61], v[60:61], v[64:65]
	v_pk_add_f32 v[58:59], v[58:59], v[62:63]
	global_store_dwordx4 v[70:71], v[58:61], off offset:64
	s_waitcnt vmcnt(13)
	s_nop 1
	v_mov_b64_e32 v[58:59], v[192:193]
	v_mov_b64_e32 v[60:61], v[194:195]
	v_pk_add_f32 v[56:57], v[56:57], v[60:61]
	v_pk_add_f32 v[54:55], v[54:55], v[58:59]
	global_store_dwordx4 v[70:71], v[54:57], off offset:512
	s_waitcnt vmcnt(12)
	s_nop 1
	v_mov_b64_e32 v[54:55], v[196:197]
	v_mov_b64_e32 v[56:57], v[198:199]
	v_pk_add_f32 v[52:53], v[52:53], v[56:57]
	v_add_co_u32_e32 v56, vcc, s68, v142
	v_pk_add_f32 v[50:51], v[50:51], v[54:55]
	s_nop 0
	v_addc_co_u32_e32 v57, vcc, 0, v143, vcc
	global_store_dwordx4 v[70:71], v[50:53], off offset:576
	v_lshl_add_u64 v[54:55], v[142:143], 0, s[42:43]
	s_waitcnt vmcnt(11)
	s_nop 1
	v_mov_b64_e32 v[50:51], v[200:201]
	v_mov_b64_e32 v[52:53], v[202:203]
	v_pk_add_f32 v[48:49], v[48:49], v[52:53]
	v_pk_add_f32 v[46:47], v[46:47], v[50:51]
	global_store_dwordx4 v[56:57], v[46:49], off
	s_waitcnt vmcnt(10)
	s_nop 1
	v_mov_b64_e32 v[46:47], v[204:205]
	v_mov_b64_e32 v[48:49], v[206:207]
	v_pk_add_f32 v[44:45], v[44:45], v[48:49]
	v_pk_add_f32 v[42:43], v[42:43], v[46:47]
	global_store_dwordx4 v[54:55], v[42:45], off offset:64
	s_waitcnt vmcnt(9)
	s_nop 1
	v_mov_b64_e32 v[42:43], v[208:209]
	v_mov_b64_e32 v[44:45], v[210:211]
	v_pk_add_f32 v[40:41], v[40:41], v[44:45]
	v_pk_add_f32 v[38:39], v[38:39], v[42:43]
	global_store_dwordx4 v[54:55], v[38:41], off offset:512
	s_waitcnt vmcnt(8)
	s_nop 1
	v_mov_b64_e32 v[38:39], v[212:213]
	v_mov_b64_e32 v[40:41], v[214:215]
	v_pk_add_f32 v[36:37], v[36:37], v[40:41]
	v_add_co_u32_e32 v40, vcc, s69, v142
	v_pk_add_f32 v[34:35], v[34:35], v[38:39]
	s_nop 0
	v_addc_co_u32_e32 v41, vcc, 0, v143, vcc
	global_store_dwordx4 v[54:55], v[34:37], off offset:576
	v_lshl_add_u64 v[38:39], v[142:143], 0, s[44:45]
	s_waitcnt vmcnt(7)
	s_nop 1
	v_mov_b64_e32 v[34:35], v[216:217]
	v_mov_b64_e32 v[36:37], v[218:219]
	v_pk_add_f32 v[32:33], v[32:33], v[36:37]
	v_pk_add_f32 v[30:31], v[30:31], v[34:35]
	global_store_dwordx4 v[40:41], v[30:33], off
	s_waitcnt vmcnt(6)
	s_nop 1
	v_mov_b64_e32 v[30:31], v[220:221]
	v_mov_b64_e32 v[32:33], v[222:223]
	v_pk_add_f32 v[28:29], v[28:29], v[32:33]
	v_pk_add_f32 v[26:27], v[26:27], v[30:31]
	global_store_dwordx4 v[38:39], v[26:29], off offset:64
	s_waitcnt vmcnt(5)
	s_nop 1
	v_mov_b64_e32 v[26:27], v[224:225]
	v_mov_b64_e32 v[28:29], v[226:227]
	v_pk_add_f32 v[24:25], v[24:25], v[28:29]
	v_pk_add_f32 v[22:23], v[22:23], v[26:27]
	global_store_dwordx4 v[38:39], v[22:25], off offset:512
	s_waitcnt vmcnt(4)
	s_nop 1
	v_mov_b64_e32 v[22:23], v[228:229]
	v_mov_b64_e32 v[24:25], v[230:231]
	v_pk_add_f32 v[20:21], v[20:21], v[24:25]
	v_add_co_u32_e32 v24, vcc, s70, v142
	v_pk_add_f32 v[18:19], v[18:19], v[22:23]
	s_nop 0
	v_addc_co_u32_e32 v25, vcc, 0, v143, vcc
	global_store_dwordx4 v[38:39], v[18:21], off offset:576
	s_and_b64 vcc, exec, s[2:3]
	v_lshl_add_u64 v[18:19], v[142:143], 0, s[26:27]
	s_waitcnt vmcnt(3)
	s_nop 1
	v_mov_b64_e32 v[20:21], v[232:233]
	v_mov_b64_e32 v[22:23], v[234:235]
	v_pk_add_f32 v[16:17], v[16:17], v[22:23]
	v_pk_add_f32 v[14:15], v[14:15], v[20:21]
	global_store_dwordx4 v[24:25], v[14:17], off
	s_waitcnt vmcnt(2)
	s_nop 1
	v_mov_b64_e32 v[14:15], v[236:237]
	v_mov_b64_e32 v[16:17], v[238:239]
	v_pk_add_f32 v[12:13], v[12:13], v[16:17]
	v_pk_add_f32 v[10:11], v[10:11], v[14:15]
	global_store_dwordx4 v[18:19], v[10:13], off offset:64
	s_waitcnt vmcnt(1)
	s_nop 1
	v_mov_b64_e32 v[10:11], v[240:241]
	v_mov_b64_e32 v[12:13], v[242:243]
	v_pk_add_f32 v[8:9], v[8:9], v[12:13]
	v_pk_add_f32 v[6:7], v[6:7], v[10:11]
	global_store_dwordx4 v[18:19], v[6:9], off offset:512
	s_waitcnt vmcnt(0)
	s_nop 1
	v_mov_b64_e32 v[6:7], v[244:245]
	v_mov_b64_e32 v[8:9], v[246:247]
	v_pk_add_f32 v[4:5], v[4:5], v[8:9]
	v_pk_add_f32 v[2:3], v[2:3], v[6:7]
	global_store_dwordx4 v[18:19], v[2:5], off offset:576
	s_cbranch_vccnz .LBB0_1078
	s_andn2_b64 vcc, exec, s[30:31]
	s_cbranch_vccnz .LBB0_1077
	s_barrier
	s_branch .LBB0_1077
